# v31 + w_up int8 transpose item order paired so both 64-byte k-halves of each 128-byte destination line are written by neighbouring waves of one workgroup
# baseline (speedup 1.0000x reference)
; __device__ __forceinline__ void ph_transpose_q8(const TrJob job, LAS unsigned* scr, int gw, int NGW, int lane) {
;     ...
;     const int ngrp = job.nrows / 64, nitems = (job.K / 64) * ngrp;
;     for (int item = gw; item < nitems; item += NGW) {
;         const int kb = item / ngrp, gq = item % ngrp, k0 = 64 * kb, r0 = 64 * gq, sb = srcbase_of(job.kind, r0);
;         const int n4 = (lane & 15) * 4; const bool inb = sb + n4 < job.N;
.LBB0_842:
	s_mul_i32 s64, s43, 0x17d06
	s_lshr_b32 s64, s64, 26
	s_mul_i32 s64, s64, 0x2b0
	s_sub_i32 s65, s43, s64
	s_and_b32 s66, s65, 1
	s_mul_i32 s66, s66, 0x158
	s_lshr_b32 s65, s65, 1
	s_add_i32 s64, s64, s66
	s_add_i32 s64, s64, s65
	s_lshl_b32 s65, s64, 6
	s_lshl_b32 s66, s64, 5
	s_mul_hi_i32 s1, s64, 0x2fa0be83
	s_lshr_b32 s6, s1, 31
	s_ashr_i32 s1, s1, 6
	s_add_i32 s1, s1, s6
	s_mul_i32 s6, s1, 0xffffaa00
	s_mul_i32 s7, s1, 0xffffd500
	s_add_i32 s45, s65, s6
	s_bfe_i32 s6, s64, 0x10001
	s_add_i32 s7, s66, s7
	s_and_b32 s6, s6, 0x2b00
	s_and_b32 s44, s7, 0xffffff80
	s_add_i32 s6, s6, s44
	s_and_b32 s7, s45, 64
	s_or_b32 s26, s6, s7
	v_cmp_lt_i32_e64 s[6:7], s26, v93
	v_cmp_ge_i32_e32 vcc, s26, v93
	s_and_saveexec_b64 s[8:9], vcc
	s_xor_b64 s[8:9], exec, s[8:9]
	s_or_saveexec_b64 s[28:29], s[8:9]
	v_mov_b32_e32 v2, 0
	v_mov_b64_e32 v[4:5], s[26:27]
	v_mov_b32_e32 v72, 0
	v_mov_b32_e32 v73, 0
	v_mov_b32_e32 v74, 0
	v_mov_b32_e32 v75, 0
	s_xor_b64 exec, exec, s[28:29]
	s_cbranch_execz .LBB0_844
	s_ashr_i32 s31, s26, 31
	s_mov_b32 s30, s26
	v_lshl_add_u64 v[4:5], s[30:31], 2, v[66:67]
	global_load_dwordx4 v[120:123], v[4:5], off
	v_mov_b64_e32 v[4:5], s[30:31]
